# cache policy: single-use residual base (x / h) loads marked non-temporal, gate loads stay cached
# baseline (speedup 1.0000x reference)
; __device__ __forceinline__ void epi_all_run(const void* Pk_, int l, int s, const f32x4 (&acc)[2][2][4][2], const pg8::Unit& u, int wr, int wc, int fr, int fq) {
;     ...
;             const float* MOD = (const float*)(ws + WS_MOD);
;             const int gidx = (s == 1) ? 2 : (s == 4 ? 5 : 8);
;             const float* base = (l == 0 && s == 1) ? A.x : A.out; float* out = A.out;
;             const float* gp = MOD + (size_t)(l * 4 + b) * NMODC + gidx * DM; const float scale = (s == 4) ? 1.0f : 0.5f;
;             const int nsite = 3 * l + (s == 1 ? 1 : (s == 4 ? 2 : 3));
;             const int col0 = u.pn * 256 + wc * 32 + 8 * fq;
;             float* slots = (float*)(ws + WS_RSP) + (size_t)nsite * M * 16;
;             f32x4 gv[2][2];
; #pragma unroll
;             for (int bj = 0; bj < 2; ++bj)
; #pragma unroll
;                 for (int n = 0; n < 2; ++n) gv[bj][n] = *(const f32x4*)(gp + col0 + bj * 128 + n * 4) * scale;
;             f32x4 bb[2][2][2];
; #pragma unroll
;             for (int bj = 0; bj < 2; ++bj)
; #pragma unroll
;                 for (int n = 0; n < 2; ++n) bb[0][bj][n] = *(const f32x4*)(base + (size_t)row0 * DM + col0 + bj * 128 + n * 4);
; #pragma unroll
;             for (int g = 0; g < 8; ++g) {
;                 const int ai = g >> 2, m = g & 3, row = row0 + ai * 128 + m * 16;
;                 if (g < 7) { const int rown = row0 + ((g + 1) >> 2) * 128 + ((g + 1) & 3) * 16;
; #pragma unroll
;                     for (int bj = 0; bj < 2; ++bj)
; #pragma unroll
;                         for (int n = 0; n < 2; ++n) bb[(g + 1) & 1][bj][n] = *(const f32x4*)(base + (size_t)rown * DM + col0 + bj * 128 + n * 4); }
;                 float ss = 0.f;
; #pragma unroll
;                 for (int bj = 0; bj < 2; ++bj)
; #pragma unroll
;                     for (int n = 0; n < 2; ++n) {
;                         const f32x4 h = bb[g & 1][bj][n] + gv[bj][n] * acc[ai][bj][m][n];
;                         *(f32x4*)(out + (size_t)row * DM + col0 + bj * 128 + n * 4) = h;
;                         ss += (h[0] * h[0] + h[1] * h[1]) + (h[2] * h[2] + h[3] * h[3]);
;                     }
;                 if (nsite < 3 * DEPTH) {
;                     ss += shx(ss, 16); ss += shx(ss, 32);
;                     if (fq == 0) __hip_atomic_store(slots + ((size_t)u.pn * M + row) * 4 + wc, ss, __ATOMIC_RELAXED, __HIP_MEMORY_SCOPE_AGENT);
.LBB0_90:
	s_andn2_b64 vcc, exec, s[46:47]
	v_or_b32_e32 v186, 16, v184
	s_cbranch_vccnz .LBB0_125
	s_ashr_i32 s20, s31, 4
	s_cmp_eq_u32 s75, 0
	s_cselect_b64 s[38:39], -1, 0
	s_cmp_eq_u32 s76, 4
	s_cselect_b64 s[46:47], -1, 0
	v_cndmask_b32_e64 v168, 0.5, 1.0, s[46:47]
	s_and_b64 s[46:47], s[46:47], exec
	s_cselect_b32 s31, s93, 0x2000
	s_cselect_b32 s50, 2, 3
	s_cmp_eq_u32 s76, 1
	s_cselect_b64 s[46:47], -1, 0
	s_and_b64 s[48:49], s[46:47], exec
	s_cselect_b32 s31, 0x800, s31
	s_cselect_b32 s48, 1, s50
	s_and_b64 s[38:39], s[38:39], s[46:47]
	s_and_b64 s[38:39], s[38:39], exec
	s_cselect_b32 s38, 0, 0xc0
	s_add_u32 s38, s4, s38
	s_addc_u32 s39, s5, 0
	s_lshl_b32 s46, s75, 2
	s_add_i32 s20, s46, s20
	s_mul_hi_i32 s46, s20, 0x9000
	s_mul_i32 s20, s20, 0x9000
	s_waitcnt lgkmcnt(0)
	s_add_u32 s20, s34, s20
	s_addc_u32 s47, s35, s46
	s_lshl_b32 s31, s31, 2
	v_lshl_or_b32 v130, s30, 8, v228
	s_add_u32 s46, s20, s31
	v_ashrrev_i32_e32 v131, 31, v130
	s_load_dwordx2 s[38:39], s[38:39], 0x0
	s_nop 0
	s_load_dwordx2 s[4:5], s[4:5], 0xc0
	s_addc_u32 s47, s47, 0
	v_lshlrev_b64 v[188:189], 2, v[130:131]
	v_lshl_add_u64 v[130:131], s[46:47], 0, v[188:189]
	s_mov_b64 s[46:47], 0x10000
	s_mov_b32 s20, 0x10000
	v_lshl_add_u64 v[132:133], v[130:131], 0, s[46:47]
	v_add_co_u32_e32 v130, vcc, s20, v130
	v_ashrrev_i32_e32 v185, 31, v184
	s_nop 0
	v_addc_co_u32_e32 v131, vcc, 0, v131, vcc
	v_lshlrev_b64 v[190:191], 12, v[184:185]
	v_ashrrev_i32_e32 v187, 31, v186
	global_load_dwordx4 v[142:145], v[130:131], off
	global_load_dwordx4 v[150:153], v[132:133], off offset:528
	global_load_dwordx4 v[154:157], v[132:133], off offset:16
	global_load_dwordx4 v[158:161], v[132:133], off offset:512
	s_waitcnt lgkmcnt(0)
	v_lshl_add_u64 v[130:131], s[38:39], 0, v[190:191]
	v_lshl_add_u64 v[206:207], s[38:39], 0, v[188:189]
	v_lshlrev_b64 v[166:167], 12, v[186:187]
	v_lshl_add_u64 v[130:131], v[130:131], 0, v[188:189]
	v_lshl_add_u64 v[134:135], v[206:207], 0, v[166:167]
	global_load_dwordx4 v[162:165], v[130:131], off nt
	global_load_dwordx4 v[208:211], v[130:131], off offset:16 nt
	global_load_dwordx4 v[212:215], v[130:131], off offset:528 nt
	global_load_dwordx4 v[230:233], v[130:131], off offset:512 nt
	global_load_dwordx4 v[138:141], v[134:135], off offset:16 nt
	global_load_dwordx4 v[146:149], v[134:135], off nt
	s_nop 0
	global_load_dwordx4 v[130:133], v[134:135], off offset:528 nt
	s_nop 0
	global_load_dwordx4 v[134:137], v[134:135], off offset:512 nt
	s_mul_i32 s75, s75, 3
	s_add_i32 s48, s48, s75
	s_ashr_i32 s49, s48, 31
	v_lshl_add_u64 v[200:201], s[4:5], 0, v[188:189]
	s_lshl_b64 s[4:5], s[48:49], 20
	s_add_u32 s4, s34, s4
	s_addc_u32 s5, s35, s5
	s_add_u32 s20, s4, 0xed00000
	s_addc_u32 s46, s5, 0
	v_lshl_add_u64 v[234:235], v[200:201], 0, v[190:191]
	s_cmp_lt_i32 s48, 6
	s_cselect_b64 s[38:39], -1, 0
	s_cmp_gt_i32 s48, 5
	s_waitcnt vmcnt(0)
	v_pk_mul_f32 v[202:203], v[168:169], v[144:145] op_sel_hi:[0,1]
	v_pk_mul_f32 v[204:205], v[168:169], v[142:143] op_sel_hi:[0,1]
	v_pk_mul_f32 v[198:199], v[168:169], v[156:157] op_sel_hi:[0,1]
	v_pk_mul_f32 v[196:197], v[168:169], v[154:155] op_sel_hi:[0,1]
	v_pk_mul_f32 v[192:193], v[168:169], v[160:161] op_sel_hi:[0,1]
	v_pk_mul_f32 v[194:195], v[168:169], v[158:159] op_sel_hi:[0,1]
	v_pk_mul_f32 v[190:191], v[168:169], v[152:153] op_sel_hi:[0,1]
	v_pk_mul_f32 v[188:189], v[168:169], v[150:151] op_sel_hi:[0,1]
	v_pk_fma_f32 v[128:129], v[128:129], v[202:203], v[164:165]
	v_pk_fma_f32 v[126:127], v[126:127], v[204:205], v[162:163]
	v_pk_fma_f32 v[124:125], v[124:125], v[198:199], v[210:211]
	v_pk_fma_f32 v[122:123], v[122:123], v[196:197], v[208:209]
	v_pk_fma_f32 v[120:121], v[120:121], v[192:193], v[232:233]
	v_pk_fma_f32 v[118:119], v[118:119], v[194:195], v[230:231]
	v_pk_fma_f32 v[116:117], v[116:117], v[190:191], v[214:215]
	v_pk_fma_f32 v[114:115], v[114:115], v[188:189], v[212:213]
	global_store_dwordx4 v[234:235], v[126:129], off
	global_store_dwordx4 v[234:235], v[122:125], off offset:16
	global_store_dwordx4 v[234:235], v[118:121], off offset:512
	global_store_dwordx4 v[234:235], v[114:117], off offset:528
	s_cbranch_scc1 .LBB0_95
	v_mul_f32_e32 v143, v127, v127
	v_fmac_f32_e32 v143, v126, v126
	v_mul_f32_e32 v142, v129, v129
	v_fmac_f32_e32 v142, v128, v128
	v_add_f32_e32 v142, v143, v142
	v_mul_f32_e32 v143, v123, v123
	v_mul_f32_e32 v144, v125, v125
	v_fmac_f32_e32 v143, v122, v122
	v_fmac_f32_e32 v144, v124, v124
	v_add_f32_e32 v143, v143, v144
	v_add_f32_e32 v142, v142, v143
	v_mul_f32_e32 v143, v119, v119
	v_mul_f32_e32 v144, v121, v121
	v_fmac_f32_e32 v143, v118, v118
	v_fmac_f32_e32 v144, v120, v120
	v_add_f32_e32 v143, v143, v144
	v_add_f32_e32 v142, v142, v143
	v_mul_f32_e32 v143, v115, v115
	v_mul_f32_e32 v144, v117, v117
	v_fmac_f32_e32 v143, v114, v114
	v_fmac_f32_e32 v144, v116, v116
	v_add_f32_e32 v143, v143, v144
	v_add_f32_e32 v142, v142, v143
	v_mov_b32_e32 v170, v142
; __device__ __forceinline__ float shx(float v, int o) { const int idx = (((int)otid() & 63) ^ o) << 2; return __builtin_bit_cast(float, __builtin_amdgcn_ds_bpermute(idx, __builtin_bit_cast(int, v))); }
; __device__ __forceinline__ void epi_all_run(const void* Pk_, int l, int s, const f32x4 (&acc)[2][2][4][2], const pg8::Unit& u, int wr, int wc, int fr, int fq) {
;     ...
;             for (int g = 0; g < 8; ++g) {
;                 const int ai = g >> 2, m = g & 3, row = row0 + ai * 128 + m * 16;
;                 if (g < 7) { const int rown = row0 + ((g + 1) >> 2) * 128 + ((g + 1) & 3) * 16;
; #pragma unroll
;                     for (int bj = 0; bj < 2; ++bj)
; #pragma unroll
;                         for (int n = 0; n < 2; ++n) bb[(g + 1) & 1][bj][n] = *(const f32x4*)(base + (size_t)rown * DM + col0 + bj * 128 + n * 4); }
;                 float ss = 0.f;
; #pragma unroll
;                 for (int bj = 0; bj < 2; ++bj)
; #pragma unroll
;                     for (int n = 0; n < 2; ++n) {
;                         const f32x4 h = bb[g & 1][bj][n] + gv[bj][n] * acc[ai][bj][m][n];
;                         *(f32x4*)(out + (size_t)row * DM + col0 + bj * 128 + n * 4) = h;
;                         ss += (h[0] * h[0] + h[1] * h[1]) + (h[2] * h[2] + h[3] * h[3]);
;                     }
;                 if (nsite < 3 * DEPTH) {
;                     ss += shx(ss, 16); ss += shx(ss, 32);
;                     if (fq == 0) __hip_atomic_store(slots + ((size_t)u.pn * M + row) * 4 + wc, ss, __ATOMIC_RELAXED, __HIP_MEMORY_SCOPE_AGENT);
.LBB0_94:
.LBB0_95:
	v_or_b32_e32 v208, 32, v184
	v_ashrrev_i32_e32 v209, 31, v208
	v_lshlrev_b64 v[212:213], 12, v[208:209]
	v_lshl_add_u64 v[150:151], v[206:207], 0, v[212:213]
	global_load_dwordx4 v[154:157], v[150:151], off offset:16 nt
	global_load_dwordx4 v[162:165], v[150:151], off nt
	s_waitcnt lgkmcnt(0)
	global_load_dwordx4 v[142:145], v[150:151], off offset:528 nt
	s_nop 0
	global_load_dwordx4 v[150:153], v[150:151], off offset:512 nt
	v_cndmask_b32_e64 v160, 0, 1, s[38:39]
	v_lshl_add_u64 v[158:159], v[200:201], 0, v[166:167]
	v_pk_fma_f32 v[112:113], v[112:113], v[202:203], v[148:149]
	v_pk_fma_f32 v[110:111], v[110:111], v[204:205], v[146:147]
	v_pk_fma_f32 v[108:109], v[108:109], v[198:199], v[140:141]
	v_pk_fma_f32 v[106:107], v[106:107], v[196:197], v[138:139]
	v_pk_fma_f32 v[104:105], v[104:105], v[192:193], v[136:137]
	v_pk_fma_f32 v[102:103], v[102:103], v[194:195], v[134:135]
	v_pk_fma_f32 v[100:101], v[100:101], v[190:191], v[132:133]
	v_pk_fma_f32 v[98:99], v[98:99], v[188:189], v[130:131]
	v_cmp_ne_u32_e64 s[4:5], 1, v160
	s_andn2_b64 vcc, exec, s[38:39]
	global_store_dwordx4 v[158:159], v[110:113], off
	global_store_dwordx4 v[158:159], v[106:109], off offset:16
	global_store_dwordx4 v[158:159], v[102:105], off offset:512
	global_store_dwordx4 v[158:159], v[98:101], off offset:528
	s_cbranch_vccnz .LBB0_99
	v_mul_f32_e32 v147, v111, v111
	v_mul_f32_e32 v139, v107, v107
	v_mul_f32_e32 v131, v99, v99
	v_fmac_f32_e32 v147, v110, v110
	v_mul_f32_e32 v146, v113, v113
	v_fmac_f32_e32 v139, v106, v106
	v_mul_f32_e32 v138, v109, v109
	v_mul_f32_e32 v135, v103, v103
	v_fmac_f32_e32 v131, v98, v98
	v_mul_f32_e32 v130, v101, v101
	v_fmac_f32_e32 v146, v112, v112
	v_fmac_f32_e32 v138, v108, v108
	v_fmac_f32_e32 v135, v102, v102
	v_mul_f32_e32 v134, v105, v105
	v_fmac_f32_e32 v130, v100, v100
	v_add_f32_e32 v146, v147, v146
	v_add_f32_e32 v138, v139, v138
	v_fmac_f32_e32 v134, v104, v104
	v_add_f32_e32 v130, v131, v130
	v_add_f32_e32 v138, v146, v138
	v_add_f32_e32 v134, v135, v134
	v_add_f32_e32 v134, v138, v134
	v_add_f32_e32 v130, v134, v130
	v_mov_b32_e32 v171, v130
.LBB0_98:
.LBB0_99:
	v_or_b32_e32 v210, 48, v184
	v_ashrrev_i32_e32 v211, 31, v210
	v_lshlrev_b64 v[214:215], 12, v[210:211]
	v_lshl_add_u64 v[134:135], v[206:207], 0, v[214:215]
	global_load_dwordx4 v[158:161], v[134:135], off offset:16 nt
	global_load_dwordx4 v[166:169], v[134:135], off nt
	s_waitcnt lgkmcnt(0)
	global_load_dwordx4 v[130:133], v[134:135], off offset:528 nt
	global_load_dwordx4 v[146:149], v[134:135], off offset:512 nt
	v_lshl_add_u64 v[212:213], v[200:201], 0, v[212:213]
	s_waitcnt vmcnt(10)
	v_pk_fma_f32 v[96:97], v[96:97], v[202:203], v[164:165]
	v_pk_fma_f32 v[94:95], v[94:95], v[204:205], v[162:163]
	v_pk_fma_f32 v[92:93], v[92:93], v[198:199], v[156:157]
	v_pk_fma_f32 v[90:91], v[90:91], v[196:197], v[154:155]
	s_waitcnt vmcnt(8)
	v_pk_fma_f32 v[88:89], v[88:89], v[192:193], v[152:153]
	v_pk_fma_f32 v[86:87], v[86:87], v[194:195], v[150:151]
	v_pk_fma_f32 v[84:85], v[84:85], v[190:191], v[144:145]
	v_pk_fma_f32 v[82:83], v[82:83], v[188:189], v[142:143]
	s_and_b64 vcc, exec, s[4:5]
	global_store_dwordx4 v[212:213], v[94:97], off
	global_store_dwordx4 v[212:213], v[90:93], off offset:16
	global_store_dwordx4 v[212:213], v[86:89], off offset:512
	global_store_dwordx4 v[212:213], v[82:85], off offset:528
	s_cbranch_vccnz .LBB0_103
	v_mul_f32_e32 v135, v95, v95
	v_fmac_f32_e32 v135, v94, v94
	v_mul_f32_e32 v134, v97, v97
	v_fmac_f32_e32 v134, v96, v96
	v_add_f32_e32 v134, v135, v134
	v_mul_f32_e32 v135, v91, v91
	v_mul_f32_e32 v136, v93, v93
	v_fmac_f32_e32 v135, v90, v90
	v_fmac_f32_e32 v136, v92, v92
	v_add_f32_e32 v135, v135, v136
	v_add_f32_e32 v134, v134, v135
	v_mul_f32_e32 v135, v87, v87
	v_mul_f32_e32 v136, v89, v89
	v_fmac_f32_e32 v135, v86, v86
	v_fmac_f32_e32 v136, v88, v88
	v_add_f32_e32 v135, v135, v136
	v_add_f32_e32 v134, v134, v135
	v_mul_f32_e32 v135, v83, v83
	v_mul_f32_e32 v136, v85, v85
	v_fmac_f32_e32 v135, v82, v82
	v_fmac_f32_e32 v136, v84, v84
	v_add_f32_e32 v135, v135, v136
	v_add_f32_e32 v134, v134, v135
	v_mov_b32_e32 v172, v134
.LBB0_102:
.LBB0_103:
	v_add_u32_e32 v208, 0x80, v184
	v_ashrrev_i32_e32 v209, 31, v208
	v_lshlrev_b64 v[212:213], 12, v[208:209]
	v_lshl_add_u64 v[138:139], v[206:207], 0, v[212:213]
	global_load_dwordx4 v[150:153], v[138:139], off offset:16 nt
	global_load_dwordx4 v[162:165], v[138:139], off nt
	s_waitcnt lgkmcnt(0)
	global_load_dwordx4 v[134:137], v[138:139], off offset:528 nt
	s_nop 0
	global_load_dwordx4 v[138:141], v[138:139], off offset:512 nt
	v_lshl_add_u64 v[214:215], v[200:201], 0, v[214:215]
	s_waitcnt vmcnt(10)
	v_pk_fma_f32 v[80:81], v[80:81], v[202:203], v[168:169]
	v_pk_fma_f32 v[78:79], v[78:79], v[204:205], v[166:167]
	v_pk_fma_f32 v[76:77], v[76:77], v[198:199], v[160:161]
	v_pk_fma_f32 v[74:75], v[74:75], v[196:197], v[158:159]
	s_waitcnt vmcnt(8)
	v_pk_fma_f32 v[72:73], v[72:73], v[192:193], v[148:149]
	v_pk_fma_f32 v[70:71], v[70:71], v[194:195], v[146:147]
	v_pk_fma_f32 v[68:69], v[68:69], v[190:191], v[132:133]
	v_pk_fma_f32 v[66:67], v[66:67], v[188:189], v[130:131]
	s_and_b64 vcc, exec, s[4:5]
	global_store_dwordx4 v[214:215], v[78:81], off
	global_store_dwordx4 v[214:215], v[74:77], off offset:16
	global_store_dwordx4 v[214:215], v[70:73], off offset:512
	global_store_dwordx4 v[214:215], v[66:69], off offset:528
	s_cbranch_vccnz .LBB0_107
	v_mul_f32_e32 v143, v79, v79
	v_fmac_f32_e32 v143, v78, v78
	v_mul_f32_e32 v142, v81, v81
	v_fmac_f32_e32 v142, v80, v80
	v_add_f32_e32 v142, v143, v142
	v_mul_f32_e32 v143, v75, v75
	v_mul_f32_e32 v144, v77, v77
	v_fmac_f32_e32 v143, v74, v74
	v_fmac_f32_e32 v144, v76, v76
	v_mul_f32_e32 v131, v67, v67
	v_add_f32_e32 v143, v143, v144
	v_fmac_f32_e32 v131, v66, v66
	v_mul_f32_e32 v130, v69, v69
	v_add_f32_e32 v142, v142, v143
	v_mul_f32_e32 v143, v71, v71
	v_mul_f32_e32 v144, v73, v73
	v_fmac_f32_e32 v130, v68, v68
	v_fmac_f32_e32 v143, v70, v70
	v_fmac_f32_e32 v144, v72, v72
	v_add_f32_e32 v130, v131, v130
	v_add_f32_e32 v143, v143, v144
	v_add_f32_e32 v142, v142, v143
	v_add_f32_e32 v130, v142, v130
	v_mov_b32_e32 v173, v130
; __device__ __forceinline__ float shx(float v, int o) { const int idx = (((int)otid() & 63) ^ o) << 2; return __builtin_bit_cast(float, __builtin_amdgcn_ds_bpermute(idx, __builtin_bit_cast(int, v))); }
; __device__ __forceinline__ void epi_all_run(const void* Pk_, int l, int s, const f32x4 (&acc)[2][2][4][2], const pg8::Unit& u, int wr, int wc, int fr, int fq) {
;     ...
;             for (int g = 0; g < 8; ++g) {
;                 const int ai = g >> 2, m = g & 3, row = row0 + ai * 128 + m * 16;
;                 if (g < 7) { const int rown = row0 + ((g + 1) >> 2) * 128 + ((g + 1) & 3) * 16;
; #pragma unroll
;                     for (int bj = 0; bj < 2; ++bj)
; #pragma unroll
;                         for (int n = 0; n < 2; ++n) bb[(g + 1) & 1][bj][n] = *(const f32x4*)(base + (size_t)rown * DM + col0 + bj * 128 + n * 4); }
;                 float ss = 0.f;
; #pragma unroll
;                 for (int bj = 0; bj < 2; ++bj)
; #pragma unroll
;                     for (int n = 0; n < 2; ++n) {
;                         const f32x4 h = bb[g & 1][bj][n] + gv[bj][n] * acc[ai][bj][m][n];
;                         *(f32x4*)(out + (size_t)row * DM + col0 + bj * 128 + n * 4) = h;
;                         ss += (h[0] * h[0] + h[1] * h[1]) + (h[2] * h[2] + h[3] * h[3]);
;                     }
;                 if (nsite < 3 * DEPTH) {
;                     ss += shx(ss, 16); ss += shx(ss, 32);
;                     if (fq == 0) __hip_atomic_store(slots + ((size_t)u.pn * M + row) * 4 + wc, ss, __ATOMIC_RELAXED, __HIP_MEMORY_SCOPE_AGENT);
.LBB0_106:
.LBB0_107:
	v_or_b32_e32 v210, 16, v208
	v_ashrrev_i32_e32 v211, 31, v210
	v_lshlrev_b64 v[214:215], 12, v[210:211]
	v_lshl_add_u64 v[142:143], v[206:207], 0, v[214:215]
	global_load_dwordx4 v[154:157], v[142:143], off offset:16 nt
	global_load_dwordx4 v[166:169], v[142:143], off nt
	s_waitcnt lgkmcnt(0)
	global_load_dwordx4 v[130:133], v[142:143], off offset:528 nt
	s_nop 0
	global_load_dwordx4 v[142:145], v[142:143], off offset:512 nt
	v_lshl_add_u64 v[158:159], v[200:201], 0, v[212:213]
	s_waitcnt vmcnt(10)
	v_pk_fma_f32 v[64:65], v[64:65], v[202:203], v[164:165]
	v_pk_fma_f32 v[62:63], v[62:63], v[204:205], v[162:163]
	v_pk_fma_f32 v[60:61], v[60:61], v[198:199], v[152:153]
	v_pk_fma_f32 v[58:59], v[58:59], v[196:197], v[150:151]
	s_waitcnt vmcnt(8)
	v_pk_fma_f32 v[56:57], v[56:57], v[192:193], v[140:141]
	v_pk_fma_f32 v[54:55], v[54:55], v[194:195], v[138:139]
	v_pk_fma_f32 v[52:53], v[52:53], v[190:191], v[136:137]
	v_pk_fma_f32 v[50:51], v[50:51], v[188:189], v[134:135]
	s_and_b64 vcc, exec, s[4:5]
	global_store_dwordx4 v[158:159], v[62:65], off
	global_store_dwordx4 v[158:159], v[58:61], off offset:16
	global_store_dwordx4 v[158:159], v[54:57], off offset:512
	global_store_dwordx4 v[158:159], v[50:53], off offset:528
	s_cbranch_vccnz .LBB0_111
	v_mul_f32_e32 v147, v63, v63
	v_fmac_f32_e32 v147, v62, v62
	v_mul_f32_e32 v146, v65, v65
	v_fmac_f32_e32 v146, v64, v64
	v_mul_f32_e32 v135, v51, v51
	v_add_f32_e32 v146, v147, v146
	v_mul_f32_e32 v147, v59, v59
	v_mul_f32_e32 v148, v61, v61
	v_mul_f32_e32 v139, v55, v55
	v_fmac_f32_e32 v135, v50, v50
	v_mul_f32_e32 v134, v53, v53
	v_fmac_f32_e32 v147, v58, v58
	v_fmac_f32_e32 v148, v60, v60
	v_fmac_f32_e32 v139, v54, v54
	v_mul_f32_e32 v138, v57, v57
	v_fmac_f32_e32 v134, v52, v52
	v_add_f32_e32 v147, v147, v148
	v_fmac_f32_e32 v138, v56, v56
	v_add_f32_e32 v134, v135, v134
	v_add_f32_e32 v146, v146, v147
	v_add_f32_e32 v138, v139, v138
	v_add_f32_e32 v138, v146, v138
	v_add_f32_e32 v134, v138, v134
	v_mov_b32_e32 v174, v134
.LBB0_110:
.LBB0_111:
	v_or_b32_e32 v162, 32, v208
	v_ashrrev_i32_e32 v163, 31, v162
	v_lshlrev_b64 v[212:213], 12, v[162:163]
	v_lshl_add_u64 v[138:139], v[206:207], 0, v[212:213]
	global_load_dwordx4 v[146:149], v[138:139], off offset:16 nt
	global_load_dwordx4 v[158:161], v[138:139], off nt
	s_waitcnt lgkmcnt(0)
	global_load_dwordx4 v[134:137], v[138:139], off offset:528 nt
	s_nop 0
	global_load_dwordx4 v[138:141], v[138:139], off offset:512 nt
	v_lshl_add_u64 v[164:165], v[200:201], 0, v[214:215]
	s_waitcnt vmcnt(10)
	v_pk_fma_f32 v[48:49], v[48:49], v[202:203], v[168:169]
	v_pk_fma_f32 v[46:47], v[46:47], v[204:205], v[166:167]
	v_pk_fma_f32 v[44:45], v[44:45], v[198:199], v[156:157]
	v_pk_fma_f32 v[42:43], v[42:43], v[196:197], v[154:155]
	s_waitcnt vmcnt(8)
	v_pk_fma_f32 v[40:41], v[40:41], v[192:193], v[144:145]
	v_pk_fma_f32 v[38:39], v[38:39], v[194:195], v[142:143]
	v_pk_fma_f32 v[36:37], v[36:37], v[190:191], v[132:133]
	v_pk_fma_f32 v[34:35], v[34:35], v[188:189], v[130:131]
	s_and_b64 vcc, exec, s[4:5]
	global_store_dwordx4 v[164:165], v[46:49], off
	global_store_dwordx4 v[164:165], v[42:45], off offset:16
	global_store_dwordx4 v[164:165], v[38:41], off offset:512
	global_store_dwordx4 v[164:165], v[34:37], off offset:528
	s_cbranch_vccnz .LBB0_115
	v_mul_f32_e32 v151, v47, v47
	v_fmac_f32_e32 v151, v46, v46
	v_mul_f32_e32 v150, v49, v49
	v_fmac_f32_e32 v150, v48, v48
	v_mul_f32_e32 v131, v35, v35
	v_add_f32_e32 v150, v151, v150
	v_mul_f32_e32 v151, v43, v43
	v_mul_f32_e32 v152, v45, v45
	v_mul_f32_e32 v143, v39, v39
	v_fmac_f32_e32 v131, v34, v34
	v_mul_f32_e32 v130, v37, v37
	v_fmac_f32_e32 v151, v42, v42
	v_fmac_f32_e32 v152, v44, v44
	v_fmac_f32_e32 v143, v38, v38
	v_mul_f32_e32 v142, v41, v41
	v_fmac_f32_e32 v130, v36, v36
	v_add_f32_e32 v151, v151, v152
	v_fmac_f32_e32 v142, v40, v40
	v_add_f32_e32 v130, v131, v130
	v_add_f32_e32 v150, v150, v151
	v_add_f32_e32 v142, v143, v142
	v_add_f32_e32 v142, v150, v142
	v_add_f32_e32 v130, v142, v130
	v_mov_b32_e32 v175, v130
.LBB0_114:
.LBB0_115:
	v_or_b32_e32 v164, 48, v208
	v_ashrrev_i32_e32 v165, 31, v164
	v_lshlrev_b64 v[166:167], 12, v[164:165]
	v_lshl_add_u64 v[142:143], v[206:207], 0, v[166:167]
	global_load_dwordx4 v[150:153], v[142:143], off offset:16 nt
	global_load_dwordx4 v[154:157], v[142:143], off nt
	s_waitcnt lgkmcnt(0)
	global_load_dwordx4 v[130:133], v[142:143], off offset:528 nt
	s_nop 0
	global_load_dwordx4 v[142:145], v[142:143], off offset:512 nt
	v_lshl_add_u64 v[168:169], v[200:201], 0, v[212:213]
	s_waitcnt vmcnt(10)
	v_pk_fma_f32 v[32:33], v[32:33], v[202:203], v[160:161]
	v_pk_fma_f32 v[30:31], v[30:31], v[204:205], v[158:159]
	v_pk_fma_f32 v[28:29], v[28:29], v[198:199], v[148:149]
	v_pk_fma_f32 v[26:27], v[26:27], v[196:197], v[146:147]
	s_waitcnt vmcnt(8)
	v_pk_fma_f32 v[24:25], v[24:25], v[192:193], v[140:141]
	v_pk_fma_f32 v[22:23], v[22:23], v[194:195], v[138:139]
	v_pk_fma_f32 v[20:21], v[20:21], v[190:191], v[136:137]
	v_pk_fma_f32 v[18:19], v[18:19], v[188:189], v[134:135]
	s_and_b64 vcc, exec, s[4:5]
	global_store_dwordx4 v[168:169], v[30:33], off
	global_store_dwordx4 v[168:169], v[26:29], off offset:16
	global_store_dwordx4 v[168:169], v[22:25], off offset:512
	global_store_dwordx4 v[168:169], v[18:21], off offset:528
	s_cbranch_vccnz .LBB0_119
	v_mul_f32_e32 v159, v31, v31
	v_mul_f32_e32 v147, v27, v27
	v_mul_f32_e32 v135, v19, v19
	v_fmac_f32_e32 v159, v30, v30
	v_mul_f32_e32 v158, v33, v33
	v_fmac_f32_e32 v147, v26, v26
	v_mul_f32_e32 v146, v29, v29
	v_mul_f32_e32 v139, v23, v23
	v_fmac_f32_e32 v135, v18, v18
	v_mul_f32_e32 v134, v21, v21
	v_fmac_f32_e32 v158, v32, v32
	v_fmac_f32_e32 v146, v28, v28
	v_fmac_f32_e32 v139, v22, v22
	v_mul_f32_e32 v138, v25, v25
	v_fmac_f32_e32 v134, v20, v20
	v_add_f32_e32 v158, v159, v158
	v_add_f32_e32 v146, v147, v146
	v_fmac_f32_e32 v138, v24, v24
	v_add_f32_e32 v134, v135, v134
	v_add_f32_e32 v146, v158, v146
	v_add_f32_e32 v138, v139, v138
	v_add_f32_e32 v138, v146, v138
	v_add_f32_e32 v134, v138, v134
	v_mov_b32_e32 v176, v134
